# v46 + relu canonicalize trim + nt on EpiRes fast-path XB/X stores (same instructions as v50), header comments document the edits
# baseline (speedup 1.0000x reference)
; DI float bflo(unsigned v) { return __uint_as_float(v << 16); }
; DI float bfhi(unsigned v) { return __uint_as_float(v & 0xffff0000u); }
; DI unsigned pk(float lo, float hi) { return pg8::cvt_pk_bf16(lo, hi); }
;     DI void operator()(const f32x4 (&acc)[2][2][4][2], const pg8::Unit& u, int wr, int wc, int fr, int fq) const {
;         const int row0 = u.pm * 256 + wr * 64 + fr, col0 = u.pn * 256 + wc * 32 + 8 * fq;
; #pragma unroll
;         for (int ai = 0; ai < 2; ++ai)
; #pragma unroll
;             for (int m = 0; m < 4; ++m) {
;                 const int row = row0 + ai * 128 + m * 16;
;                 float sq = 0.f;
; #pragma unroll
;                 for (int bj = 0; bj < 2; ++bj) {
;                     const size_t off = (size_t)row * D + col0 + bj * 128;
;                     f32x4 a, b;
;                     if (mid) { a = *(const f32x4*)(Xin + off); b = *(const f32x4*)(Xin + off + 4); }
;                     else { const u32x4 h = *(const u32x4*)(XB + off); a = (f32x4){bflo(h.x), bfhi(h.x), bflo(h.y), bfhi(h.y)}; b = (f32x4){bflo(h.z), bfhi(h.z), bflo(h.w), bfhi(h.w)}; }
;                     a += acc[ai][bj][m][0] * scale; b += acc[ai][bj][m][1] * scale;
;                     if (X) { *(f32x4*)(X + off) = a; *(f32x4*)(X + off + 4) = b; }
;                     sq += (a[0] * a[0] + a[1] * a[1]) + (a[2] * a[2] + a[3] * a[3]) + (b[0] * b[0] + b[1] * b[1]) + (b[2] * b[2] + b[3] * b[3]);
;                     u32x4 w; w.x = pk(a[0], a[1]); w.y = pk(a[2], a[3]); w.z = pk(b[0], b[1]); w.w = pk(b[2], b[3]);
;                     *(u32x4*)(XB + off) = w;
.Lepi_fast:
	v_lshl_add_u32 v150, s40, 8, v137
	v_lshl_or_b32 v148, s84, 8, v167
	v_lshl_add_u32 v152, v150, 10, v148
	v_lshlrev_b32_e32 v152, 1, v152
	global_load_dwordx4 v[170:173], v152, s[72:73]
	global_load_dwordx4 v[174:177], v152, s[72:73] offset:256
	v_add_u32_e32 v153, 0x8000, v152
	global_load_dwordx4 v[178:181], v153, s[72:73]
	global_load_dwordx4 v[182:185], v153, s[72:73] offset:256
	v_add_u32_e32 v153, 0x10000, v152
	global_load_dwordx4 v[186:189], v153, s[72:73]
	global_load_dwordx4 v[190:193], v153, s[72:73] offset:256
	v_add_u32_e32 v153, 0x18000, v152
	global_load_dwordx4 v[214:217], v153, s[72:73]
	global_load_dwordx4 v[218:221], v153, s[72:73] offset:256
	v_add_u32_e32 v153, 0x40000, v152
	global_load_dwordx4 v[222:225], v153, s[72:73]
	global_load_dwordx4 v[226:229], v153, s[72:73] offset:256
	v_add_u32_e32 v153, 0x48000, v152
	global_load_dwordx4 v[230:233], v153, s[72:73]
	global_load_dwordx4 v[234:237], v153, s[72:73] offset:256
	v_add_u32_e32 v153, 0x50000, v152
	global_load_dwordx4 v[238:241], v153, s[72:73]
	global_load_dwordx4 v[242:245], v153, s[72:73] offset:256
	v_add_u32_e32 v153, 0x58000, v152
	global_load_dwordx4 v[128:131], v153, s[72:73]
	global_load_dwordx4 v[132:135], v153, s[72:73] offset:256
	s_lshl_b32 s82, s84, 4
	s_lshl_b32 s83, s8, 2
	s_add_i32 s82, s82, s83
	v_lshl_add_u32 v148, v150, 6, s82
	v_xor_b32_e32 v194, 16, v198
	v_xor_b32_e32 v195, 32, v198
	v_lshlrev_b32_e32 v194, 2, v194
	v_lshlrev_b32_e32 v195, 2, v195
	v_mov_b32_e32 v153, v152
	v_lshlrev_b32_e32 v149, 1, v153
	s_waitcnt vmcnt(15)
	v_lshlrev_b32_e32 v154, 16, v170
	v_and_b32_e32 v155, 0xffff0000, v170
	v_lshlrev_b32_e32 v164, 16, v171
	v_and_b32_e32 v165, 0xffff0000, v171
	v_lshlrev_b32_e32 v170, 16, v172
	v_and_b32_e32 v171, 0xffff0000, v172
	v_lshlrev_b32_e32 v172, 16, v173
	v_and_b32_e32 v173, 0xffff0000, v173
	v_pk_add_f32 v[124:125], v[124:125], v[154:155]
	v_pk_add_f32 v[126:127], v[126:127], v[164:165]
	v_pk_add_f32 v[120:121], v[120:121], v[170:171]
	v_pk_add_f32 v[122:123], v[122:123], v[172:173]
	s_and_b64 vcc, exec, s[76:77]
	s_cbranch_vccz .Lepi_nox_0
	global_store_dwordx4 v149, v[124:127], s[20:21] offset:0 nt
	global_store_dwordx4 v149, v[120:123], s[20:21] offset:16 nt
.Lepi_nox_0:
	v_cvt_pk_bf16_f32 v170, v124, v125
	v_cvt_pk_bf16_f32 v171, v126, v127
	v_cvt_pk_bf16_f32 v172, v120, v121
	v_cvt_pk_bf16_f32 v173, v122, v123
	global_store_dwordx4 v153, v[170:173], s[72:73] nt
	v_mul_f32_e32 v150, v125, v125
	v_fmac_f32_e32 v150, v124, v124
	v_mul_f32_e32 v151, v127, v127
	v_fmac_f32_e32 v151, v126, v126
	v_mul_f32_e32 v246, v121, v121
	v_add_f32_e32 v151, v150, v151
	v_fmac_f32_e32 v246, v120, v120
	v_add_f32_e32 v151, v246, v151
	v_mul_f32_e32 v246, v123, v123
	v_fmac_f32_e32 v246, v122, v122
	v_add_f32_e32 v247, v246, v151
	s_waitcnt vmcnt(15)
	v_lshlrev_b32_e32 v154, 16, v174
	v_and_b32_e32 v155, 0xffff0000, v174
	v_lshlrev_b32_e32 v164, 16, v175
	v_and_b32_e32 v165, 0xffff0000, v175
	v_lshlrev_b32_e32 v174, 16, v176
	v_and_b32_e32 v175, 0xffff0000, v176
	v_lshlrev_b32_e32 v176, 16, v177
	v_and_b32_e32 v177, 0xffff0000, v177
	v_pk_add_f32 v[116:117], v[116:117], v[154:155]
	v_pk_add_f32 v[118:119], v[118:119], v[164:165]
	v_pk_add_f32 v[112:113], v[112:113], v[174:175]
	v_pk_add_f32 v[114:115], v[114:115], v[176:177]
	s_and_b64 vcc, exec, s[76:77]
	s_cbranch_vccz .Lepi_nox_1
	global_store_dwordx4 v149, v[116:119], s[20:21] offset:512 nt
	global_store_dwordx4 v149, v[112:115], s[20:21] offset:528 nt
.Lepi_nox_1:
	v_cvt_pk_bf16_f32 v174, v116, v117
	v_cvt_pk_bf16_f32 v175, v118, v119
	v_cvt_pk_bf16_f32 v176, v112, v113
	v_cvt_pk_bf16_f32 v177, v114, v115
	global_store_dwordx4 v153, v[174:177], s[72:73] offset:256 nt
	v_mul_f32_e32 v150, v117, v117
	v_mul_f32_e32 v151, v119, v119
	v_fmac_f32_e32 v150, v116, v116
	v_fmac_f32_e32 v151, v118, v118
	v_add_f32_e32 v150, v150, v151
	v_mul_f32_e32 v151, v113, v113
	v_fmac_f32_e32 v151, v112, v112
	v_add_f32_e32 v150, v151, v150
	v_mul_f32_e32 v151, v115, v115
	v_fmac_f32_e32 v151, v114, v114
	v_add_f32_e32 v150, v151, v150
	v_add_f32_e32 v150, v247, v150
	v_mov_b32_e32 v124, v150
	v_add_u32_e32 v153, 0x8000, v152
	v_lshlrev_b32_e32 v149, 1, v153
	s_waitcnt vmcnt(15)
	v_lshlrev_b32_e32 v154, 16, v178
	v_and_b32_e32 v155, 0xffff0000, v178
	v_lshlrev_b32_e32 v164, 16, v179
	v_and_b32_e32 v165, 0xffff0000, v179
	v_lshlrev_b32_e32 v178, 16, v180
	v_and_b32_e32 v179, 0xffff0000, v180
	v_lshlrev_b32_e32 v180, 16, v181
	v_and_b32_e32 v181, 0xffff0000, v181
	v_pk_add_f32 v[108:109], v[108:109], v[154:155]
	v_pk_add_f32 v[110:111], v[110:111], v[164:165]
	v_pk_add_f32 v[104:105], v[104:105], v[178:179]
	v_pk_add_f32 v[106:107], v[106:107], v[180:181]
	s_and_b64 vcc, exec, s[76:77]
	s_cbranch_vccz .Lepi_nox_2
	global_store_dwordx4 v149, v[108:111], s[20:21] offset:0 nt
	global_store_dwordx4 v149, v[104:107], s[20:21] offset:16 nt
.Lepi_nox_2:
	v_cvt_pk_bf16_f32 v178, v108, v109
	v_cvt_pk_bf16_f32 v179, v110, v111
	v_cvt_pk_bf16_f32 v180, v104, v105
	v_cvt_pk_bf16_f32 v181, v106, v107
	global_store_dwordx4 v153, v[178:181], s[72:73] nt
	v_mul_f32_e32 v150, v109, v109
	v_fmac_f32_e32 v150, v108, v108
	v_mul_f32_e32 v151, v111, v111
	v_fmac_f32_e32 v151, v110, v110
	v_mul_f32_e32 v246, v105, v105
	v_add_f32_e32 v151, v150, v151
	v_fmac_f32_e32 v246, v104, v104
	v_add_f32_e32 v151, v246, v151
	v_mul_f32_e32 v246, v107, v107
	v_fmac_f32_e32 v246, v106, v106
	v_add_f32_e32 v247, v246, v151
	s_waitcnt vmcnt(15)
	v_lshlrev_b32_e32 v154, 16, v182
	v_and_b32_e32 v155, 0xffff0000, v182
	v_lshlrev_b32_e32 v164, 16, v183
	v_and_b32_e32 v165, 0xffff0000, v183
	v_lshlrev_b32_e32 v182, 16, v184
	v_and_b32_e32 v183, 0xffff0000, v184
	v_lshlrev_b32_e32 v184, 16, v185
	v_and_b32_e32 v185, 0xffff0000, v185
	v_pk_add_f32 v[100:101], v[100:101], v[154:155]
	v_pk_add_f32 v[102:103], v[102:103], v[164:165]
	v_pk_add_f32 v[96:97], v[96:97], v[182:183]
	v_pk_add_f32 v[98:99], v[98:99], v[184:185]
	s_and_b64 vcc, exec, s[76:77]
	s_cbranch_vccz .Lepi_nox_3
	global_store_dwordx4 v149, v[100:103], s[20:21] offset:512 nt
	global_store_dwordx4 v149, v[96:99], s[20:21] offset:528 nt
; DI float bflo(unsigned v) { return __uint_as_float(v << 16); }
; DI float bfhi(unsigned v) { return __uint_as_float(v & 0xffff0000u); }
; DI unsigned pk(float lo, float hi) { return pg8::cvt_pk_bf16(lo, hi); }
;     DI void operator()(const f32x4 (&acc)[2][2][4][2], const pg8::Unit& u, int wr, int wc, int fr, int fq) const {
;     ...
;                 for (int bj = 0; bj < 2; ++bj) {
;                     const size_t off = (size_t)row * D + col0 + bj * 128;
;                     f32x4 a, b;
;                     if (mid) { a = *(const f32x4*)(Xin + off); b = *(const f32x4*)(Xin + off + 4); }
;                     else { const u32x4 h = *(const u32x4*)(XB + off); a = (f32x4){bflo(h.x), bfhi(h.x), bflo(h.y), bfhi(h.y)}; b = (f32x4){bflo(h.z), bfhi(h.z), bflo(h.w), bfhi(h.w)}; }
;                     a += acc[ai][bj][m][0] * scale; b += acc[ai][bj][m][1] * scale;
;                     if (X) { *(f32x4*)(X + off) = a; *(f32x4*)(X + off + 4) = b; }
;                     sq += (a[0] * a[0] + a[1] * a[1]) + (a[2] * a[2] + a[3] * a[3]) + (b[0] * b[0] + b[1] * b[1]) + (b[2] * b[2] + b[3] * b[3]);
;                     u32x4 w; w.x = pk(a[0], a[1]); w.y = pk(a[2], a[3]); w.z = pk(b[0], b[1]); w.w = pk(b[2], b[3]);
;                     *(u32x4*)(XB + off) = w;
.Lepi_nox_3:
	v_cvt_pk_bf16_f32 v182, v100, v101
	v_cvt_pk_bf16_f32 v183, v102, v103
	v_cvt_pk_bf16_f32 v184, v96, v97
	v_cvt_pk_bf16_f32 v185, v98, v99
	global_store_dwordx4 v153, v[182:185], s[72:73] offset:256 nt
	v_mul_f32_e32 v150, v101, v101
	v_mul_f32_e32 v151, v103, v103
	v_fmac_f32_e32 v150, v100, v100
	v_fmac_f32_e32 v151, v102, v102
	v_add_f32_e32 v150, v150, v151
	v_mul_f32_e32 v151, v97, v97
	v_fmac_f32_e32 v151, v96, v96
	v_add_f32_e32 v150, v151, v150
	v_mul_f32_e32 v151, v99, v99
	v_fmac_f32_e32 v151, v98, v98
	v_add_f32_e32 v150, v151, v150
	v_add_f32_e32 v150, v247, v150
	v_mov_b32_e32 v108, v150
	v_add_u32_e32 v153, 0x10000, v152
	v_lshlrev_b32_e32 v149, 1, v153
	s_waitcnt vmcnt(15)
	v_lshlrev_b32_e32 v154, 16, v186
	v_and_b32_e32 v155, 0xffff0000, v186
	v_lshlrev_b32_e32 v164, 16, v187
	v_and_b32_e32 v165, 0xffff0000, v187
	v_lshlrev_b32_e32 v186, 16, v188
	v_and_b32_e32 v187, 0xffff0000, v188
	v_lshlrev_b32_e32 v188, 16, v189
	v_and_b32_e32 v189, 0xffff0000, v189
	v_pk_add_f32 v[92:93], v[92:93], v[154:155]
	v_pk_add_f32 v[94:95], v[94:95], v[164:165]
	v_pk_add_f32 v[88:89], v[88:89], v[186:187]
	v_pk_add_f32 v[90:91], v[90:91], v[188:189]
	s_and_b64 vcc, exec, s[76:77]
	s_cbranch_vccz .Lepi_nox_4
	global_store_dwordx4 v149, v[92:95], s[20:21] offset:0 nt
	global_store_dwordx4 v149, v[88:91], s[20:21] offset:16 nt
.Lepi_nox_4:
	v_cvt_pk_bf16_f32 v186, v92, v93
	v_cvt_pk_bf16_f32 v187, v94, v95
	v_cvt_pk_bf16_f32 v188, v88, v89
	v_cvt_pk_bf16_f32 v189, v90, v91
	global_store_dwordx4 v153, v[186:189], s[72:73] nt
	v_mul_f32_e32 v150, v93, v93
	v_fmac_f32_e32 v150, v92, v92
	v_mul_f32_e32 v151, v95, v95
	v_fmac_f32_e32 v151, v94, v94
	v_mul_f32_e32 v246, v89, v89
	v_add_f32_e32 v151, v150, v151
	v_fmac_f32_e32 v246, v88, v88
	v_add_f32_e32 v151, v246, v151
	v_mul_f32_e32 v246, v91, v91
	v_fmac_f32_e32 v246, v90, v90
	v_add_f32_e32 v247, v246, v151
	s_waitcnt vmcnt(15)
	v_lshlrev_b32_e32 v154, 16, v190
	v_and_b32_e32 v155, 0xffff0000, v190
	v_lshlrev_b32_e32 v164, 16, v191
	v_and_b32_e32 v165, 0xffff0000, v191
	v_lshlrev_b32_e32 v190, 16, v192
	v_and_b32_e32 v191, 0xffff0000, v192
	v_lshlrev_b32_e32 v192, 16, v193
	v_and_b32_e32 v193, 0xffff0000, v193
	v_pk_add_f32 v[84:85], v[84:85], v[154:155]
	v_pk_add_f32 v[86:87], v[86:87], v[164:165]
	v_pk_add_f32 v[80:81], v[80:81], v[190:191]
	v_pk_add_f32 v[82:83], v[82:83], v[192:193]
	s_and_b64 vcc, exec, s[76:77]
	s_cbranch_vccz .Lepi_nox_5
	global_store_dwordx4 v149, v[84:87], s[20:21] offset:512 nt
	global_store_dwordx4 v149, v[80:83], s[20:21] offset:528 nt
.Lepi_nox_5:
	v_cvt_pk_bf16_f32 v190, v84, v85
	v_cvt_pk_bf16_f32 v191, v86, v87
	v_cvt_pk_bf16_f32 v192, v80, v81
	v_cvt_pk_bf16_f32 v193, v82, v83
	global_store_dwordx4 v153, v[190:193], s[72:73] offset:256 nt
	v_mul_f32_e32 v150, v85, v85
	v_mul_f32_e32 v151, v87, v87
	v_fmac_f32_e32 v150, v84, v84
	v_fmac_f32_e32 v151, v86, v86
	v_add_f32_e32 v150, v150, v151
	v_mul_f32_e32 v151, v81, v81
	v_fmac_f32_e32 v151, v80, v80
	v_add_f32_e32 v150, v151, v150
	v_mul_f32_e32 v151, v83, v83
	v_fmac_f32_e32 v151, v82, v82
	v_add_f32_e32 v150, v151, v150
	v_add_f32_e32 v150, v247, v150
	v_mov_b32_e32 v92, v150
	v_add_u32_e32 v153, 0x18000, v152
	v_lshlrev_b32_e32 v149, 1, v153
	s_waitcnt vmcnt(15)
	v_lshlrev_b32_e32 v154, 16, v214
	v_and_b32_e32 v155, 0xffff0000, v214
	v_lshlrev_b32_e32 v164, 16, v215
	v_and_b32_e32 v165, 0xffff0000, v215
	v_lshlrev_b32_e32 v214, 16, v216
	v_and_b32_e32 v215, 0xffff0000, v216
	v_lshlrev_b32_e32 v216, 16, v217
	v_and_b32_e32 v217, 0xffff0000, v217
	v_pk_add_f32 v[76:77], v[76:77], v[154:155]
	v_pk_add_f32 v[78:79], v[78:79], v[164:165]
	v_pk_add_f32 v[72:73], v[72:73], v[214:215]
	v_pk_add_f32 v[74:75], v[74:75], v[216:217]
	s_and_b64 vcc, exec, s[76:77]
	s_cbranch_vccz .Lepi_nox_6
	global_store_dwordx4 v149, v[76:79], s[20:21] offset:0 nt
	global_store_dwordx4 v149, v[72:75], s[20:21] offset:16 nt
.Lepi_nox_6:
	v_cvt_pk_bf16_f32 v214, v76, v77
	v_cvt_pk_bf16_f32 v215, v78, v79
	v_cvt_pk_bf16_f32 v216, v72, v73
	v_cvt_pk_bf16_f32 v217, v74, v75
	global_store_dwordx4 v153, v[214:217], s[72:73] nt
	v_mul_f32_e32 v150, v77, v77
	v_fmac_f32_e32 v150, v76, v76
	v_mul_f32_e32 v151, v79, v79
	v_fmac_f32_e32 v151, v78, v78
	v_mul_f32_e32 v246, v73, v73
	v_add_f32_e32 v151, v150, v151
	v_fmac_f32_e32 v246, v72, v72
	v_add_f32_e32 v151, v246, v151
	v_mul_f32_e32 v246, v75, v75
	v_fmac_f32_e32 v246, v74, v74
	v_add_f32_e32 v247, v246, v151
	s_waitcnt vmcnt(15)
	v_lshlrev_b32_e32 v154, 16, v218
	v_and_b32_e32 v155, 0xffff0000, v218
	v_lshlrev_b32_e32 v164, 16, v219
	v_and_b32_e32 v165, 0xffff0000, v219
	v_lshlrev_b32_e32 v218, 16, v220
	v_and_b32_e32 v219, 0xffff0000, v220
	v_lshlrev_b32_e32 v220, 16, v221
	v_and_b32_e32 v221, 0xffff0000, v221
	v_pk_add_f32 v[68:69], v[68:69], v[154:155]
	v_pk_add_f32 v[70:71], v[70:71], v[164:165]
	v_pk_add_f32 v[64:65], v[64:65], v[218:219]
	v_pk_add_f32 v[66:67], v[66:67], v[220:221]
	s_and_b64 vcc, exec, s[76:77]
	s_cbranch_vccz .Lepi_nox_7
	global_store_dwordx4 v149, v[68:71], s[20:21] offset:512 nt
	global_store_dwordx4 v149, v[64:67], s[20:21] offset:528 nt
; DI float bflo(unsigned v) { return __uint_as_float(v << 16); }
; DI float bfhi(unsigned v) { return __uint_as_float(v & 0xffff0000u); }
; DI unsigned pk(float lo, float hi) { return pg8::cvt_pk_bf16(lo, hi); }
;     DI void operator()(const f32x4 (&acc)[2][2][4][2], const pg8::Unit& u, int wr, int wc, int fr, int fq) const {
;     ...
;         for (int ai = 0; ai < 2; ++ai)
; #pragma unroll
;             for (int m = 0; m < 4; ++m) {
;                 const int row = row0 + ai * 128 + m * 16;
;                 float sq = 0.f;
; #pragma unroll
;                 for (int bj = 0; bj < 2; ++bj) {
;                     const size_t off = (size_t)row * D + col0 + bj * 128;
;                     f32x4 a, b;
;                     if (mid) { a = *(const f32x4*)(Xin + off); b = *(const f32x4*)(Xin + off + 4); }
;                     else { const u32x4 h = *(const u32x4*)(XB + off); a = (f32x4){bflo(h.x), bfhi(h.x), bflo(h.y), bfhi(h.y)}; b = (f32x4){bflo(h.z), bfhi(h.z), bflo(h.w), bfhi(h.w)}; }
;                     a += acc[ai][bj][m][0] * scale; b += acc[ai][bj][m][1] * scale;
;                     if (X) { *(f32x4*)(X + off) = a; *(f32x4*)(X + off + 4) = b; }
;                     sq += (a[0] * a[0] + a[1] * a[1]) + (a[2] * a[2] + a[3] * a[3]) + (b[0] * b[0] + b[1] * b[1]) + (b[2] * b[2] + b[3] * b[3]);
;                     u32x4 w; w.x = pk(a[0], a[1]); w.y = pk(a[2], a[3]); w.z = pk(b[0], b[1]); w.w = pk(b[2], b[3]);
;                     *(u32x4*)(XB + off) = w;
.Lepi_nox_7:
	v_cvt_pk_bf16_f32 v218, v68, v69
	v_cvt_pk_bf16_f32 v219, v70, v71
	v_cvt_pk_bf16_f32 v220, v64, v65
	v_cvt_pk_bf16_f32 v221, v66, v67
	global_store_dwordx4 v153, v[218:221], s[72:73] offset:256 nt
	v_mul_f32_e32 v150, v69, v69
	v_mul_f32_e32 v151, v71, v71
	v_fmac_f32_e32 v150, v68, v68
	v_fmac_f32_e32 v151, v70, v70
	v_add_f32_e32 v150, v150, v151
	v_mul_f32_e32 v151, v65, v65
	v_fmac_f32_e32 v151, v64, v64
	v_add_f32_e32 v150, v151, v150
	v_mul_f32_e32 v151, v67, v67
	v_fmac_f32_e32 v151, v66, v66
	v_add_f32_e32 v150, v151, v150
	v_add_f32_e32 v150, v247, v150
	v_mov_b32_e32 v76, v150
	v_add_u32_e32 v153, 0x40000, v152
	v_lshlrev_b32_e32 v149, 1, v153
	v_add_u32_e32 v148, 0x2000, v148
	s_waitcnt vmcnt(15)
	v_lshlrev_b32_e32 v154, 16, v222
	v_and_b32_e32 v155, 0xffff0000, v222
	v_lshlrev_b32_e32 v164, 16, v223
	v_and_b32_e32 v165, 0xffff0000, v223
	v_lshlrev_b32_e32 v222, 16, v224
	v_and_b32_e32 v223, 0xffff0000, v224
	v_lshlrev_b32_e32 v224, 16, v225
	v_and_b32_e32 v225, 0xffff0000, v225
	v_pk_add_f32 v[60:61], v[60:61], v[154:155]
	v_pk_add_f32 v[62:63], v[62:63], v[164:165]
	v_pk_add_f32 v[56:57], v[56:57], v[222:223]
	v_pk_add_f32 v[58:59], v[58:59], v[224:225]
	s_and_b64 vcc, exec, s[76:77]
	s_cbranch_vccz .Lepi_nox_8
	global_store_dwordx4 v149, v[60:63], s[20:21] offset:0 nt
	global_store_dwordx4 v149, v[56:59], s[20:21] offset:16 nt
.Lepi_nox_8:
	v_cvt_pk_bf16_f32 v222, v60, v61
	v_cvt_pk_bf16_f32 v223, v62, v63
	v_cvt_pk_bf16_f32 v224, v56, v57
	v_cvt_pk_bf16_f32 v225, v58, v59
	global_store_dwordx4 v153, v[222:225], s[72:73] nt
	v_mul_f32_e32 v150, v61, v61
	v_fmac_f32_e32 v150, v60, v60
	v_mul_f32_e32 v151, v63, v63
	v_fmac_f32_e32 v151, v62, v62
	v_mul_f32_e32 v246, v57, v57
	v_add_f32_e32 v151, v150, v151
	v_fmac_f32_e32 v246, v56, v56
	v_add_f32_e32 v151, v246, v151
	v_mul_f32_e32 v246, v59, v59
	v_fmac_f32_e32 v246, v58, v58
	v_add_f32_e32 v247, v246, v151
	s_waitcnt vmcnt(15)
	v_lshlrev_b32_e32 v154, 16, v226
	v_and_b32_e32 v155, 0xffff0000, v226
	v_lshlrev_b32_e32 v164, 16, v227
	v_and_b32_e32 v165, 0xffff0000, v227
	v_lshlrev_b32_e32 v226, 16, v228
	v_and_b32_e32 v227, 0xffff0000, v228
	v_lshlrev_b32_e32 v228, 16, v229
	v_and_b32_e32 v229, 0xffff0000, v229
	v_pk_add_f32 v[52:53], v[52:53], v[154:155]
	v_pk_add_f32 v[54:55], v[54:55], v[164:165]
	v_pk_add_f32 v[48:49], v[48:49], v[226:227]
	v_pk_add_f32 v[50:51], v[50:51], v[228:229]
	s_and_b64 vcc, exec, s[76:77]
	s_cbranch_vccz .Lepi_nox_9
	global_store_dwordx4 v149, v[52:55], s[20:21] offset:512 nt
	global_store_dwordx4 v149, v[48:51], s[20:21] offset:528 nt
.Lepi_nox_9:
	v_cvt_pk_bf16_f32 v226, v52, v53
	v_cvt_pk_bf16_f32 v227, v54, v55
	v_cvt_pk_bf16_f32 v228, v48, v49
	v_cvt_pk_bf16_f32 v229, v50, v51
	global_store_dwordx4 v153, v[226:229], s[72:73] offset:256 nt
	v_mul_f32_e32 v150, v53, v53
	v_mul_f32_e32 v151, v55, v55
	v_fmac_f32_e32 v150, v52, v52
	v_fmac_f32_e32 v151, v54, v54
	v_add_f32_e32 v150, v150, v151
	v_mul_f32_e32 v151, v49, v49
	v_fmac_f32_e32 v151, v48, v48
	v_add_f32_e32 v150, v151, v150
	v_mul_f32_e32 v151, v51, v51
	v_fmac_f32_e32 v151, v50, v50
	v_add_f32_e32 v150, v151, v150
	v_add_f32_e32 v150, v247, v150
	v_mov_b32_e32 v60, v150
	v_add_u32_e32 v153, 0x48000, v152
	v_lshlrev_b32_e32 v149, 1, v153
	s_waitcnt vmcnt(15)
	v_lshlrev_b32_e32 v154, 16, v230
	v_and_b32_e32 v155, 0xffff0000, v230
	v_lshlrev_b32_e32 v164, 16, v231
	v_and_b32_e32 v165, 0xffff0000, v231
	v_lshlrev_b32_e32 v230, 16, v232
	v_and_b32_e32 v231, 0xffff0000, v232
	v_lshlrev_b32_e32 v232, 16, v233
	v_and_b32_e32 v233, 0xffff0000, v233
	v_pk_add_f32 v[44:45], v[44:45], v[154:155]
	v_pk_add_f32 v[46:47], v[46:47], v[164:165]
	v_pk_add_f32 v[40:41], v[40:41], v[230:231]
	v_pk_add_f32 v[42:43], v[42:43], v[232:233]
	s_and_b64 vcc, exec, s[76:77]
	s_cbranch_vccz .Lepi_nox_10
	global_store_dwordx4 v149, v[44:47], s[20:21] offset:0 nt
	global_store_dwordx4 v149, v[40:43], s[20:21] offset:16 nt
.Lepi_nox_10:
	v_cvt_pk_bf16_f32 v230, v44, v45
	v_cvt_pk_bf16_f32 v231, v46, v47
	v_cvt_pk_bf16_f32 v232, v40, v41
	v_cvt_pk_bf16_f32 v233, v42, v43
	global_store_dwordx4 v153, v[230:233], s[72:73] nt
	v_mul_f32_e32 v150, v45, v45
	v_fmac_f32_e32 v150, v44, v44
	v_mul_f32_e32 v151, v47, v47
	v_fmac_f32_e32 v151, v46, v46
	v_mul_f32_e32 v246, v41, v41
	v_add_f32_e32 v151, v150, v151
	v_fmac_f32_e32 v246, v40, v40
	v_add_f32_e32 v151, v246, v151
	v_mul_f32_e32 v246, v43, v43
	v_fmac_f32_e32 v246, v42, v42
	v_add_f32_e32 v247, v246, v151
	s_waitcnt vmcnt(15)
	v_lshlrev_b32_e32 v154, 16, v234
	v_and_b32_e32 v155, 0xffff0000, v234
	v_lshlrev_b32_e32 v164, 16, v235
	v_and_b32_e32 v165, 0xffff0000, v235
	v_lshlrev_b32_e32 v234, 16, v236
	v_and_b32_e32 v235, 0xffff0000, v236
	v_lshlrev_b32_e32 v236, 16, v237
	v_and_b32_e32 v237, 0xffff0000, v237
	v_pk_add_f32 v[36:37], v[36:37], v[154:155]
	v_pk_add_f32 v[38:39], v[38:39], v[164:165]
	v_pk_add_f32 v[32:33], v[32:33], v[234:235]
	v_pk_add_f32 v[34:35], v[34:35], v[236:237]
	s_and_b64 vcc, exec, s[76:77]
	s_cbranch_vccz .Lepi_nox_11
	global_store_dwordx4 v149, v[36:39], s[20:21] offset:512 nt
	global_store_dwordx4 v149, v[32:35], s[20:21] offset:528 nt
; DI float bflo(unsigned v) { return __uint_as_float(v << 16); }
; DI float bfhi(unsigned v) { return __uint_as_float(v & 0xffff0000u); }
; DI unsigned pk(float lo, float hi) { return pg8::cvt_pk_bf16(lo, hi); }
;     DI void operator()(const f32x4 (&acc)[2][2][4][2], const pg8::Unit& u, int wr, int wc, int fr, int fq) const {
;     ...
;                 for (int bj = 0; bj < 2; ++bj) {
;                     const size_t off = (size_t)row * D + col0 + bj * 128;
;                     f32x4 a, b;
;                     if (mid) { a = *(const f32x4*)(Xin + off); b = *(const f32x4*)(Xin + off + 4); }
;                     else { const u32x4 h = *(const u32x4*)(XB + off); a = (f32x4){bflo(h.x), bfhi(h.x), bflo(h.y), bfhi(h.y)}; b = (f32x4){bflo(h.z), bfhi(h.z), bflo(h.w), bfhi(h.w)}; }
;                     a += acc[ai][bj][m][0] * scale; b += acc[ai][bj][m][1] * scale;
;                     if (X) { *(f32x4*)(X + off) = a; *(f32x4*)(X + off + 4) = b; }
;                     sq += (a[0] * a[0] + a[1] * a[1]) + (a[2] * a[2] + a[3] * a[3]) + (b[0] * b[0] + b[1] * b[1]) + (b[2] * b[2] + b[3] * b[3]);
;                     u32x4 w; w.x = pk(a[0], a[1]); w.y = pk(a[2], a[3]); w.z = pk(b[0], b[1]); w.w = pk(b[2], b[3]);
;                     *(u32x4*)(XB + off) = w;
.Lepi_nox_11:
	v_cvt_pk_bf16_f32 v234, v36, v37
	v_cvt_pk_bf16_f32 v235, v38, v39
	v_cvt_pk_bf16_f32 v236, v32, v33
	v_cvt_pk_bf16_f32 v237, v34, v35
	global_store_dwordx4 v153, v[234:237], s[72:73] offset:256 nt
	v_mul_f32_e32 v150, v37, v37
	v_mul_f32_e32 v151, v39, v39
	v_fmac_f32_e32 v150, v36, v36
	v_fmac_f32_e32 v151, v38, v38
	v_add_f32_e32 v150, v150, v151
	v_mul_f32_e32 v151, v33, v33
	v_fmac_f32_e32 v151, v32, v32
	v_add_f32_e32 v150, v151, v150
	v_mul_f32_e32 v151, v35, v35
	v_fmac_f32_e32 v151, v34, v34
	v_add_f32_e32 v150, v151, v150
	v_add_f32_e32 v150, v247, v150
	v_mov_b32_e32 v44, v150
	v_add_u32_e32 v153, 0x50000, v152
	v_lshlrev_b32_e32 v149, 1, v153
	s_waitcnt vmcnt(15)
	v_lshlrev_b32_e32 v154, 16, v238
	v_and_b32_e32 v155, 0xffff0000, v238
	v_lshlrev_b32_e32 v164, 16, v239
	v_and_b32_e32 v165, 0xffff0000, v239
	v_lshlrev_b32_e32 v238, 16, v240
	v_and_b32_e32 v239, 0xffff0000, v240
	v_lshlrev_b32_e32 v240, 16, v241
	v_and_b32_e32 v241, 0xffff0000, v241
	v_pk_add_f32 v[28:29], v[28:29], v[154:155]
	v_pk_add_f32 v[30:31], v[30:31], v[164:165]
	v_pk_add_f32 v[24:25], v[24:25], v[238:239]
	v_pk_add_f32 v[26:27], v[26:27], v[240:241]
	s_and_b64 vcc, exec, s[76:77]
	s_cbranch_vccz .Lepi_nox_12
	global_store_dwordx4 v149, v[28:31], s[20:21] offset:0 nt
	global_store_dwordx4 v149, v[24:27], s[20:21] offset:16 nt
.Lepi_nox_12:
	v_cvt_pk_bf16_f32 v238, v28, v29
	v_cvt_pk_bf16_f32 v239, v30, v31
	v_cvt_pk_bf16_f32 v240, v24, v25
	v_cvt_pk_bf16_f32 v241, v26, v27
	global_store_dwordx4 v153, v[238:241], s[72:73] nt
	v_mul_f32_e32 v150, v29, v29
	v_fmac_f32_e32 v150, v28, v28
	v_mul_f32_e32 v151, v31, v31
	v_fmac_f32_e32 v151, v30, v30
	v_mul_f32_e32 v246, v25, v25
	v_add_f32_e32 v151, v150, v151
	v_fmac_f32_e32 v246, v24, v24
	v_add_f32_e32 v151, v246, v151
	v_mul_f32_e32 v246, v27, v27
	v_fmac_f32_e32 v246, v26, v26
	v_add_f32_e32 v247, v246, v151
	s_waitcnt vmcnt(15)
	v_lshlrev_b32_e32 v154, 16, v242
	v_and_b32_e32 v155, 0xffff0000, v242
	v_lshlrev_b32_e32 v164, 16, v243
	v_and_b32_e32 v165, 0xffff0000, v243
	v_lshlrev_b32_e32 v242, 16, v244
	v_and_b32_e32 v243, 0xffff0000, v244
	v_lshlrev_b32_e32 v244, 16, v245
	v_and_b32_e32 v245, 0xffff0000, v245
	v_pk_add_f32 v[20:21], v[20:21], v[154:155]
	v_pk_add_f32 v[22:23], v[22:23], v[164:165]
	v_pk_add_f32 v[16:17], v[16:17], v[242:243]
	v_pk_add_f32 v[18:19], v[18:19], v[244:245]
	s_and_b64 vcc, exec, s[76:77]
	s_cbranch_vccz .Lepi_nox_13
	global_store_dwordx4 v149, v[20:23], s[20:21] offset:512 nt
	global_store_dwordx4 v149, v[16:19], s[20:21] offset:528 nt
.Lepi_nox_13:
	v_cvt_pk_bf16_f32 v242, v20, v21
	v_cvt_pk_bf16_f32 v243, v22, v23
	v_cvt_pk_bf16_f32 v244, v16, v17
	v_cvt_pk_bf16_f32 v245, v18, v19
	global_store_dwordx4 v153, v[242:245], s[72:73] offset:256 nt
	v_mul_f32_e32 v150, v21, v21
	v_mul_f32_e32 v151, v23, v23
	v_fmac_f32_e32 v150, v20, v20
	v_fmac_f32_e32 v151, v22, v22
	v_add_f32_e32 v150, v150, v151
	v_mul_f32_e32 v151, v17, v17
	v_fmac_f32_e32 v151, v16, v16
	v_add_f32_e32 v150, v151, v150
	v_mul_f32_e32 v151, v19, v19
	v_fmac_f32_e32 v151, v18, v18
	v_add_f32_e32 v150, v151, v150
	v_add_f32_e32 v150, v247, v150
	v_mov_b32_e32 v28, v150
	v_add_u32_e32 v153, 0x58000, v152
	v_lshlrev_b32_e32 v149, 1, v153
	s_waitcnt vmcnt(15)
	v_lshlrev_b32_e32 v154, 16, v128
	v_and_b32_e32 v155, 0xffff0000, v128
	v_lshlrev_b32_e32 v164, 16, v129
	v_and_b32_e32 v165, 0xffff0000, v129
	v_lshlrev_b32_e32 v128, 16, v130
	v_and_b32_e32 v129, 0xffff0000, v130
	v_lshlrev_b32_e32 v130, 16, v131
	v_and_b32_e32 v131, 0xffff0000, v131
	v_pk_add_f32 v[12:13], v[12:13], v[154:155]
	v_pk_add_f32 v[14:15], v[14:15], v[164:165]
	v_pk_add_f32 v[8:9], v[8:9], v[128:129]
	v_pk_add_f32 v[10:11], v[10:11], v[130:131]
	s_and_b64 vcc, exec, s[76:77]
	s_cbranch_vccz .Lepi_nox_14
	global_store_dwordx4 v149, v[12:15], s[20:21] offset:0 nt
	global_store_dwordx4 v149, v[8:11], s[20:21] offset:16 nt
; DI float bflo(unsigned v) { return __uint_as_float(v << 16); }
; DI float bfhi(unsigned v) { return __uint_as_float(v & 0xffff0000u); }
; DI unsigned pk(float lo, float hi) { return pg8::cvt_pk_bf16(lo, hi); }
;     DI void operator()(const f32x4 (&acc)[2][2][4][2], const pg8::Unit& u, int wr, int wc, int fr, int fq) const {
;     ...
;                 for (int bj = 0; bj < 2; ++bj) {
;                     const size_t off = (size_t)row * D + col0 + bj * 128;
;                     f32x4 a, b;
;                     if (mid) { a = *(const f32x4*)(Xin + off); b = *(const f32x4*)(Xin + off + 4); }
;                     else { const u32x4 h = *(const u32x4*)(XB + off); a = (f32x4){bflo(h.x), bfhi(h.x), bflo(h.y), bfhi(h.y)}; b = (f32x4){bflo(h.z), bfhi(h.z), bflo(h.w), bfhi(h.w)}; }
;                     a += acc[ai][bj][m][0] * scale; b += acc[ai][bj][m][1] * scale;
;                     if (X) { *(f32x4*)(X + off) = a; *(f32x4*)(X + off + 4) = b; }
;                     sq += (a[0] * a[0] + a[1] * a[1]) + (a[2] * a[2] + a[3] * a[3]) + (b[0] * b[0] + b[1] * b[1]) + (b[2] * b[2] + b[3] * b[3]);
;                     u32x4 w; w.x = pk(a[0], a[1]); w.y = pk(a[2], a[3]); w.z = pk(b[0], b[1]); w.w = pk(b[2], b[3]);
;                     *(u32x4*)(XB + off) = w;
;                 }
;                 sq += __shfl_xor(sq, 16); sq += __shfl_xor(sq, 32);
;                 if (fq == 0) ssq_out[(size_t)row * 16 + u.pn * 4 + wc] = sq;
.Lepi_nox_14:
	v_cvt_pk_bf16_f32 v128, v12, v13
	v_cvt_pk_bf16_f32 v129, v14, v15
	v_cvt_pk_bf16_f32 v130, v8, v9
	v_cvt_pk_bf16_f32 v131, v10, v11
	global_store_dwordx4 v153, v[128:131], s[72:73] nt
	v_mul_f32_e32 v150, v13, v13
	v_fmac_f32_e32 v150, v12, v12
	v_mul_f32_e32 v151, v15, v15
	v_fmac_f32_e32 v151, v14, v14
	v_mul_f32_e32 v246, v9, v9
	v_add_f32_e32 v151, v150, v151
	v_fmac_f32_e32 v246, v8, v8
	v_add_f32_e32 v151, v246, v151
	v_mul_f32_e32 v246, v11, v11
	v_fmac_f32_e32 v246, v10, v10
	v_add_f32_e32 v247, v246, v151
	s_waitcnt vmcnt(15)
	v_lshlrev_b32_e32 v154, 16, v132
	v_and_b32_e32 v155, 0xffff0000, v132
	v_lshlrev_b32_e32 v164, 16, v133
	v_and_b32_e32 v165, 0xffff0000, v133
	v_lshlrev_b32_e32 v132, 16, v134
	v_and_b32_e32 v133, 0xffff0000, v134
	v_lshlrev_b32_e32 v134, 16, v135
	v_and_b32_e32 v135, 0xffff0000, v135
	v_pk_add_f32 v[4:5], v[4:5], v[154:155]
	v_pk_add_f32 v[6:7], v[6:7], v[164:165]
	v_pk_add_f32 v[0:1], v[0:1], v[132:133]
	v_pk_add_f32 v[2:3], v[2:3], v[134:135]
	s_and_b64 vcc, exec, s[76:77]
	s_cbranch_vccz .Lepi_nox_15
	global_store_dwordx4 v149, v[4:7], s[20:21] offset:512 nt
	global_store_dwordx4 v149, v[0:3], s[20:21] offset:528 nt
.Lepi_nox_15:
	v_cvt_pk_bf16_f32 v132, v4, v5
	v_cvt_pk_bf16_f32 v133, v6, v7
	v_cvt_pk_bf16_f32 v134, v0, v1
	v_cvt_pk_bf16_f32 v135, v2, v3
	global_store_dwordx4 v153, v[132:135], s[72:73] offset:256 nt
	v_mul_f32_e32 v150, v5, v5
	v_mul_f32_e32 v151, v7, v7
	v_fmac_f32_e32 v150, v4, v4
	v_fmac_f32_e32 v151, v6, v6
	v_add_f32_e32 v150, v150, v151
	v_mul_f32_e32 v151, v1, v1
	v_fmac_f32_e32 v151, v0, v0
	v_add_f32_e32 v150, v151, v150
	v_mul_f32_e32 v151, v3, v3
	v_fmac_f32_e32 v151, v2, v2
	v_add_f32_e32 v150, v151, v150
	v_add_f32_e32 v150, v247, v150
	v_mov_b32_e32 v12, v150
	ds_bpermute_b32 v120, v194, v124
	ds_bpermute_b32 v104, v194, v108
	ds_bpermute_b32 v88, v194, v92
	ds_bpermute_b32 v72, v194, v76
	ds_bpermute_b32 v56, v194, v60
	ds_bpermute_b32 v40, v194, v44
	ds_bpermute_b32 v24, v194, v28
	ds_bpermute_b32 v8, v194, v12
	s_waitcnt lgkmcnt(0)
	v_add_f32_e32 v124, v124, v120
	v_add_f32_e32 v108, v108, v104
	v_add_f32_e32 v92, v92, v88
	v_add_f32_e32 v76, v76, v72
	v_add_f32_e32 v60, v60, v56
	v_add_f32_e32 v44, v44, v40
	v_add_f32_e32 v28, v28, v24
	v_add_f32_e32 v12, v12, v8
	ds_bpermute_b32 v120, v195, v124
	ds_bpermute_b32 v104, v195, v108
	ds_bpermute_b32 v88, v195, v92
	ds_bpermute_b32 v72, v195, v76
	ds_bpermute_b32 v56, v195, v60
	ds_bpermute_b32 v40, v195, v44
	ds_bpermute_b32 v24, v195, v28
	ds_bpermute_b32 v8, v195, v12
	s_waitcnt lgkmcnt(0)
	v_add_f32_e32 v124, v124, v120
	v_add_f32_e32 v108, v108, v104
	v_add_f32_e32 v92, v92, v88
	v_add_f32_e32 v76, v76, v72
	v_add_f32_e32 v60, v60, v56
	v_add_f32_e32 v44, v44, v40
	v_add_f32_e32 v28, v28, v24
	v_add_f32_e32 v12, v12, v8
	s_and_saveexec_b64 s[82:83], s[36:37]
	v_add_u32_e32 v148, 0xffffe000, v148
	global_store_dword v148, v124, s[24:25] offset:0
	global_store_dword v148, v108, s[24:25] offset:1024
	global_store_dword v148, v92, s[24:25] offset:2048
	global_store_dword v148, v76, s[24:25] offset:3072
	v_add_u32_e32 v148, 0x2000, v148
	global_store_dword v148, v60, s[24:25] offset:0
	global_store_dword v148, v44, s[24:25] offset:1024
	global_store_dword v148, v28, s[24:25] offset:2048
	global_store_dword v148, v12, s[24:25] offset:3072
	s_or_b64 exec, exec, s[82:83]
	s_branch .Lepi_done
